# memory-attention reorder: sample-first workgroups chosen by bit 3 of the workgroup id (half of every XCD) instead of bit 0
# speedup vs baseline: 1.0035x; 1.0035x over previous
; #define LAS __attribute__((address_space(3)))
; template <bool SAMPLE>
; __device__ __forceinline__ void mem_unit(const Params& p, int l, LAS unsigned char* lds, int unit, int tid, int wave, int lane) {
;     const bf16* MQ = (const bf16*)(p.ws + W_MQ); bf16* MO = (bf16*)(p.ws + W_MO);
;     LAS bf16* Kl = (LAS bf16*)lds; LAS bf16* Vt = (LAS bf16*)(lds + MEM_VOFF);
;     int b, h, qt;
;     if (!SAMPLE) { qt = unit & 15; h = (unit >> 4) & 3; b = unit >> 6; } else { h = unit & 3; b = unit >> 2; qt = 0; }
;     {
;         const int sub = tid & 15;
;         float kg[8]; pg8::ld8f(p.in[I_MKG] + l * 128 + 8 * sub, kg);
; __global__ void __launch_bounds__(NTHR, 2) fwd_megakernel(Params p) {
;     ...
;         { PHASE_IDS
;         for (int rep = 0; rep < REP_LIGHT * REP_MEM; ++rep)
;         for (int u = bx; u < 256 + 512; u += G) { if (u < 256) mem_unit<false>(p, l, lds, u, tid, wave, lane); else mem_unit<true>(p, l, lds, u - 256, tid, wave, lane); } }
.LBB0_594:
	s_or_b64 exec, exec, s[0:1]
	v_readlane_b32 s0, v240, 14
	s_waitcnt lgkmcnt(0)
	v_mov_b32_e32 v0, v216
	v_readlane_b32 s1, v240, 15
	s_barrier
	s_and_b64 vcc, exec, s[0:1]
	v_readfirstlane_b32 s0, v0
	s_cbranch_vccnz .LBB0_633
	s_cmp_lt_u32 s0, 64
	s_cselect_b64 s[4:5], -1, 0
	s_ashr_i32 s0, s0, 2
	s_and_b32 s6, s0, -16
	s_ashr_i32 s7, s6, 31
	s_add_u32 s28, s94, 0x1a300000
	s_addc_u32 s29, s95, 0
	v_lshlrev_b32_e32 v1, 3, v0
	s_add_u32 s12, s92, 0xaade000
	v_and_b32_e32 v80, 0x78, v1
	v_readlane_b32 s0, v239, 14
	s_addc_u32 s13, s93, 0
	v_ashrrev_i32_e32 v81, 4, v0
	v_and_b32_e32 v94, 15, v0
	v_bfe_u32 v95, v0, 4, 2
	v_mov_b32_e32 v83, 0
	v_lshlrev_b32_e32 v82, 2, v80
	v_readlane_b32 s1, v239, 15
	v_lshlrev_b32_e32 v0, 1, v80
	s_add_u32 s14, s92, 0xaede000
	v_lshl_add_u64 v[84:85], s[0:1], 0, v[82:83]
	s_mov_b32 s11, 0
	v_add_u32_e32 v96, 0, v0
	v_add_u32_e32 v97, s90, v0
	v_lshl_add_u64 v[86:87], s[48:49], 0, v[82:83]
	s_addc_u32 s15, s93, 0
	s_movk_i32 s30, 0x110
	v_mov_b32_e32 v98, 0x358637bd
	s_mov_b32 s31, 0x800000
	s_mov_b32 s33, 0xff800000
	v_mbcnt_hi_u32_b32 v99, -1, v217
	s_mov_b32 s34, s63
	s_mov_b32 s35, s63
	v_readlane_b32 s98, v240, 1
	s_cmpk_eq_u32 s98, 0x100
	s_cselect_b32 s99, 1, 0
	s_lshr_b32 s98, s63, 3
	s_and_b32 s99, s99, s98
	s_and_b32 s99, s99, 1
	s_lshl_b32 s98, s99, 8
	s_add_i32 s35, s35, s98
	s_mov_b32 s34, s35
	s_mul_i32 s99, s99, 0x300
	s_cmp_lg_u32 s99, 0
	s_cselect_b32 s98, s35, -1
	s_nop 0
	s_nop 0
	s_nop 0
	s_nop 0
	s_nop 0
	s_nop 0
	s_nop 0
	s_nop 0
	s_nop 0
	s_nop 0
	s_nop 0
	s_nop 0
	s_nop 0
	s_branch .LBB0_597

; #define LAS __attribute__((address_space(3)))
; template <bool SAMPLE>
; __device__ __forceinline__ void mem_unit(const Params& p, int l, LAS unsigned char* lds, int unit, int tid, int wave, int lane) {
;     const bf16* MQ = (const bf16*)(p.ws + W_MQ); bf16* MO = (bf16*)(p.ws + W_MO);
;     LAS bf16* Kl = (LAS bf16*)lds; LAS bf16* Vt = (LAS bf16*)(lds + MEM_VOFF);
;     int b, h, qt;
;     if (!SAMPLE) { qt = unit & 15; h = (unit >> 4) & 3; b = unit >> 6; } else { h = unit & 3; b = unit >> 2; qt = 0; }
;     {
;         const int sub = tid & 15;
;         float kg[8]; pg8::ld8f(p.in[I_MKG] + l * 128 + 8 * sub, kg);
; __global__ void __launch_bounds__(NTHR, 2) fwd_megakernel(Params p) {
;     ...
;         { PHASE_IDS
;         for (int rep = 0; rep < REP_LIGHT * REP_MEM; ++rep)
;         for (int u = bx; u < 256 + 512; u += G) { if (u < 256) mem_unit<false>(p, l, lds, u, tid, wave, lane); else mem_unit<true>(p, l, lds, u - 256, tid, wave, lane); } }
.LBB0_2725:
	s_or_b64 exec, exec, s[0:1]
	v_readlane_b32 s0, v240, 14
	s_waitcnt lgkmcnt(0)
	v_mov_b32_e32 v0, v216
	v_readlane_b32 s1, v240, 15
	s_barrier
	s_and_b64 vcc, exec, s[0:1]
	v_readfirstlane_b32 s0, v0
	s_cbranch_vccnz .LBB0_2764
	s_cmp_lt_u32 s0, 64
	s_cselect_b64 s[6:7], -1, 0
	s_ashr_i32 s0, s0, 2
	s_and_b32 s4, s0, -16
	s_ashr_i32 s5, s4, 31
	v_lshlrev_b32_e32 v1, 3, v0
	s_add_u32 s12, s92, 0xaade000
	v_and_b32_e32 v80, 0x78, v1
	v_readlane_b32 s0, v239, 14
	s_addc_u32 s13, s93, 0
	v_ashrrev_i32_e32 v81, 4, v0
	s_waitcnt vmcnt(0)
	v_and_b32_e32 v94, 15, v0
	v_bfe_u32 v95, v0, 4, 2
	v_mov_b32_e32 v83, 0
	v_lshlrev_b32_e32 v82, 2, v80
	v_readlane_b32 s1, v239, 15
	v_lshlrev_b32_e32 v0, 1, v80
	s_add_u32 s14, s92, 0xaede000
	v_lshl_add_u64 v[84:85], s[0:1], 0, v[82:83]
	s_mov_b32 s11, 0
	v_add_u32_e32 v96, 0, v0
	v_add_u32_e32 v97, s90, v0
	v_lshl_add_u64 v[86:87], s[48:49], 0, v[82:83]
	s_addc_u32 s15, s93, 0
	s_movk_i32 s22, 0x110
	v_mov_b32_e32 v98, 0x358637bd
	s_mov_b32 s23, 0x800000
	s_mov_b32 s24, 0xff800000
	v_mbcnt_hi_u32_b32 v99, -1, v217
	s_mov_b32 s25, s63
	s_mov_b32 s26, s63
	v_readlane_b32 s98, v240, 1
	s_cmpk_eq_u32 s98, 0x100
	s_cselect_b32 s99, 1, 0
	s_lshr_b32 s98, s63, 3
	s_and_b32 s99, s99, s98
	s_and_b32 s99, s99, 1
	s_lshl_b32 s98, s99, 8
	s_add_i32 s26, s26, s98
	s_mov_b32 s25, s26
	s_mul_i32 s99, s99, 0x300
	s_cmp_lg_u32 s99, 0
	s_cselect_b32 s98, s26, -1
	s_nop 0
	s_nop 0
	s_nop 0
	s_nop 0
	s_nop 0
	s_nop 0
	s_nop 0
	s_nop 0
	s_nop 0
	s_nop 0
	s_nop 0
	s_nop 0
	s_nop 0
	s_branch .LBB0_2728
